# GEMM K-loop: B0 fragment ds_reads moved from the 12-read load phases into the P4/P8 MMA interval (8/4/8/4 LDS read balance) + tile-head pre-read
# speedup vs baseline: 1.0261x; 1.0261x over previous
; #define PG8_STAGE(bufoff, gbase, voff) do { _Pragma("unroll") for (int _i = 0; _i < 2; ++_i) \
;     __builtin_amdgcn_global_load_lds((const unsigned*)((const char*)(gbase) + (voff)[_i]), (LAS unsigned*)(lds + (bufoff) + ldsw + _i * 8192), 16, 0, 0); } while (0)
; #define PG8_LDA(dst, b, h) do { _Pragma("unroll") for (int m = 0; m < 4; ++m) _Pragma("unroll") for (int k = 0; k < 2; ++k) dst[m][k] = *(const LAS bf16x8*)(lds + PG8_SA(b, h) + aoff + m * 2048 + k * 1024); } while (0)
; #define PG8_LDB(dst, b, h) do { _Pragma("unroll") for (int n = 0; n < 2; ++n) _Pragma("unroll") for (int k = 0; k < 2; ++k) dst[n][k] = *(const LAS bf16x8*)(lds + PG8_SB(b, h) + boff + n * 2048 + k * 1024); } while (0)
; #define PG8_WAIT_V(n) asm volatile("s_waitcnt vmcnt(" #n ")" ::: "memory")
; #define PG8_WAIT_L(n) asm volatile("s_waitcnt lgkmcnt(" #n ")" ::: "memory")
; #define PG8_BAR __builtin_amdgcn_s_barrier()
; #define PG8_SCHED __builtin_amdgcn_sched_barrier(0)
; template <class Epi>
; __device__ __forceinline__ void gemm_phase(LAS unsigned char* lds, const Gemm g, const StaticOrder& S, const Epi& E) {
;     ...
;     for (int t = 0; t < nt; t += 2) {
;       const bool last = (t == nt - 2);
;       const char* a1 = cA + (size_t)(t + 1) * kstep;
;       const char* a2 = last ? nA : cA + (size_t)(t + 2) * kstep; const char* b2 = last ? nB : cB + (size_t)(t + 2) * kstep;
;       const char* a3 = a2 + kstep; const char* b3 = b2 + kstep;
;       PG8_LDB(B0, 0, 0); PG8_SCHED; PG8_LDA(At, 0, 0); PG8_STAGE(PG8_SA(1, 1), a1 + hstep, voffA);
;       PG8_WAIT_L(8); PG8_BAR; PG8_WAIT_L(0); PG8_MMA(0, 0, At, B0); PG8_BAR; PG8_SCHED;
;       PG8_LDB(B1, 0, 1); PG8_STAGE(PG8_SB(0, 0), b2, voffB);
;       PG8_BAR; PG8_WAIT_L(0); PG8_MMA(0, 1, At, B1); PG8_BAR;
;       PG8_LDA(At, 0, 1); PG8_STAGE(PG8_SA(0, 0), a2, voffA);
;       PG8_BAR; PG8_WAIT_L(0); PG8_MMA(1, 0, At, B0); PG8_BAR; PG8_SCHED;
;       PG8_STAGE(PG8_SB(0, 1), b2 + hstep, voffB);
;       PG8_WAIT_V(6); PG8_BAR; PG8_MMA(1, 1, At, B1); PG8_BAR;
;     ...
; #pragma unroll
;     for (int a = 0; a < 2; ++a)
; #pragma unroll
;       for (int b = 0; b < 2; ++b)
; #pragma unroll
;         for (int m = 0; m < 4; ++m)
; #pragma unroll
;           for (int n = 0; n < 2; ++n) acc[a][b][m][n] = (f32x4){0.f, 0.f, 0.f, 0.f};
;     cur = nxt; cA = nA; cB = nB; ++ui;
.LBB0_55:
	v_add_u32_e32 v80, 0x10000, v187
	ds_read_b128 v[130:133], v80
	ds_read_b128 v[134:137], v80 offset:1024
	ds_read_b128 v[138:141], v80 offset:2048
	ds_read_b128 v[142:145], v80 offset:3072
	s_add_u32 s74, s12, 0x100
	s_addc_u32 s75, s13, 0
	s_add_u32 s0, s10, 0x80
	v_mov_b64_e32 v[0:1], 0
	v_mov_b64_e32 v[2:3], 0
	v_mov_b64_e32 v[4:5], 0
	v_mov_b64_e32 v[6:7], 0
	v_mov_b64_e32 v[8:9], 0
	v_mov_b64_e32 v[10:11], 0
	v_mov_b64_e32 v[12:13], 0
	v_mov_b64_e32 v[14:15], 0
	v_mov_b64_e32 v[16:17], 0
	v_mov_b64_e32 v[18:19], 0
	v_mov_b64_e32 v[20:21], 0
	v_mov_b64_e32 v[22:23], 0
	v_mov_b64_e32 v[24:25], 0
	v_mov_b64_e32 v[26:27], 0
	v_mov_b64_e32 v[28:29], 0
	v_mov_b64_e32 v[30:31], 0
	v_mov_b64_e32 v[32:33], 0
	v_mov_b64_e32 v[34:35], 0
	v_mov_b64_e32 v[36:37], 0
	v_mov_b64_e32 v[38:39], 0
	v_mov_b64_e32 v[40:41], 0
	v_mov_b64_e32 v[42:43], 0
	v_mov_b64_e32 v[44:45], 0
	v_mov_b64_e32 v[46:47], 0
	v_mov_b64_e32 v[48:49], 0
	v_mov_b64_e32 v[50:51], 0
	v_mov_b64_e32 v[52:53], 0
	v_mov_b64_e32 v[54:55], 0
	v_mov_b64_e32 v[56:57], 0
	v_mov_b64_e32 v[58:59], 0
	v_mov_b64_e32 v[60:61], 0
	v_mov_b64_e32 v[62:63], 0
	v_mov_b64_e32 v[64:65], 0
	v_mov_b64_e32 v[66:67], 0
	v_mov_b64_e32 v[68:69], 0
	v_mov_b64_e32 v[70:71], 0
	v_mov_b64_e32 v[72:73], 0
	v_mov_b64_e32 v[74:75], 0
	v_mov_b64_e32 v[76:77], 0
	v_mov_b64_e32 v[78:79], 0
	v_mov_b64_e32 v[82:83], 0
	v_mov_b64_e32 v[84:85], 0
	v_mov_b64_e32 v[86:87], 0
	v_mov_b64_e32 v[88:89], 0
	v_mov_b64_e32 v[90:91], 0
	v_mov_b64_e32 v[92:93], 0
	v_mov_b64_e32 v[94:95], 0
	v_mov_b64_e32 v[96:97], 0
	v_mov_b64_e32 v[98:99], 0
	v_mov_b64_e32 v[100:101], 0
	v_mov_b64_e32 v[102:103], 0
	v_mov_b64_e32 v[104:105], 0
	v_mov_b64_e32 v[106:107], 0
	v_mov_b64_e32 v[108:109], 0
	v_mov_b64_e32 v[110:111], 0
	v_mov_b64_e32 v[112:113], 0
	v_mov_b64_e32 v[114:115], 0
	v_mov_b64_e32 v[116:117], 0
	v_mov_b64_e32 v[118:119], 0
	v_mov_b64_e32 v[120:121], 0
	v_mov_b64_e32 v[122:123], 0
	v_mov_b64_e32 v[124:125], 0
	v_mov_b64_e32 v[126:127], 0
	v_mov_b64_e32 v[128:129], 0
	s_addc_u32 s1, s11, 0
	s_mov_b32 s10, 0
.LBB0_56:
	s_add_i32 s76, s10, 2
	s_add_u32 s12, s0, 0x80
	s_addc_u32 s11, s1, 0
	s_add_i32 s77, 0, 0x10000
	s_cmp_eq_u32 s21, s10
	s_cselect_b32 s10, s18, s12
	s_cselect_b32 s11, s19, s11
	s_cselect_b32 s13, s17, s75
	s_cselect_b32 s12, s16, s74
	v_lshl_add_u64 v[194:195], s[0:1], 0, v[172:173]
	s_add_i32 m0, s15, 0xc000
	ds_read_b128 v[146:149], v189
	ds_read_b128 v[150:153], v189 offset:1024
	ds_read_b128 v[154:157], v189 offset:2048
	ds_read_b128 v[158:161], v189 offset:3072
	ds_read_b128 v[174:177], v189 offset:4096
	ds_read_b128 v[178:181], v189 offset:5120
	ds_read_b128 v[182:185], v189 offset:6144
	ds_read_b128 v[190:193], v189 offset:7168
	global_load_lds_dwordx4 v[194:195], off
	v_lshl_add_u64 v[194:195], s[0:1], 0, v[170:171]
	s_add_i32 m0, s15, 0xe000
	s_nop 0
	global_load_lds_dwordx4 v[194:195], off
	s_waitcnt lgkmcnt(8)
	s_barrier
	s_waitcnt lgkmcnt(0)
	s_waitcnt lgkmcnt(0)
	v_mfma_f32_16x16x32_bf16 v[126:129], v[130:133], v[146:149], v[126:129]
	v_mfma_f32_16x16x32_bf16 v[122:125], v[138:141], v[146:149], v[122:125]
	v_mfma_f32_16x16x32_bf16 v[118:121], v[130:133], v[154:157], v[118:121]
	v_mfma_f32_16x16x32_bf16 v[114:117], v[138:141], v[154:157], v[114:117]
	v_mfma_f32_16x16x32_bf16 v[110:113], v[130:133], v[174:177], v[110:113]
	v_mfma_f32_16x16x32_bf16 v[106:109], v[138:141], v[174:177], v[106:109]
	v_mfma_f32_16x16x32_bf16 v[102:105], v[130:133], v[182:185], v[102:105]
	v_mfma_f32_16x16x32_bf16 v[98:101], v[138:141], v[182:185], v[98:101]
	v_mfma_f32_16x16x32_bf16 v[126:129], v[134:137], v[150:153], v[126:129]
	v_mfma_f32_16x16x32_bf16 v[122:125], v[142:145], v[150:153], v[122:125]
	v_mfma_f32_16x16x32_bf16 v[118:121], v[134:137], v[158:161], v[118:121]
	v_mfma_f32_16x16x32_bf16 v[114:117], v[142:145], v[158:161], v[114:117]
	v_mfma_f32_16x16x32_bf16 v[110:113], v[134:137], v[178:181], v[110:113]
	v_mfma_f32_16x16x32_bf16 v[106:109], v[142:145], v[178:181], v[106:109]
	v_mfma_f32_16x16x32_bf16 v[102:105], v[134:137], v[190:193], v[102:105]
	v_mfma_f32_16x16x32_bf16 v[98:101], v[142:145], v[190:193], v[98:101]
	s_barrier
	s_add_i32 s78, 0, 0x14000
	s_add_i32 s77, s77, s14
	v_add_u32_e32 v80, s78, v187
	v_lshl_add_u64 v[210:211], s[12:13], 0, v[164:165]
	s_mov_b32 m0, s77
	ds_read_b128 v[194:197], v80
	ds_read_b128 v[198:201], v80 offset:1024
	ds_read_b128 v[202:205], v80 offset:2048
	ds_read_b128 v[206:209], v80 offset:3072
	global_load_lds_dwordx4 v[210:211], off
	v_lshl_add_u64 v[212:213], s[12:13], 0, v[168:169]
	s_add_i32 m0, s77, 0x2000
	s_nop 0
	global_load_lds_dwordx4 v[212:213], off
	s_barrier
	s_waitcnt lgkmcnt(0)
	s_waitcnt lgkmcnt(0)
	v_mfma_f32_16x16x32_bf16 v[60:63], v[194:197], v[146:149], v[60:63]
	v_mfma_f32_16x16x32_bf16 v[56:59], v[202:205], v[146:149], v[56:59]
	v_mfma_f32_16x16x32_bf16 v[52:55], v[194:197], v[154:157], v[52:55]
	v_mfma_f32_16x16x32_bf16 v[48:51], v[202:205], v[154:157], v[48:51]
	v_mfma_f32_16x16x32_bf16 v[44:47], v[194:197], v[174:177], v[44:47]
	v_mfma_f32_16x16x32_bf16 v[40:43], v[202:205], v[174:177], v[40:43]
	v_mfma_f32_16x16x32_bf16 v[36:39], v[194:197], v[182:185], v[36:39]
	v_mfma_f32_16x16x32_bf16 v[32:35], v[202:205], v[182:185], v[32:35]
	v_mfma_f32_16x16x32_bf16 v[60:63], v[198:201], v[150:153], v[60:63]
	v_mfma_f32_16x16x32_bf16 v[56:59], v[206:209], v[150:153], v[56:59]
	v_mfma_f32_16x16x32_bf16 v[52:55], v[198:201], v[158:161], v[52:55]
	v_mfma_f32_16x16x32_bf16 v[48:51], v[206:209], v[158:161], v[48:51]
	v_mfma_f32_16x16x32_bf16 v[44:47], v[198:201], v[178:181], v[44:47]
	v_mfma_f32_16x16x32_bf16 v[40:43], v[206:209], v[178:181], v[40:43]
	v_mfma_f32_16x16x32_bf16 v[36:39], v[198:201], v[190:193], v[36:39]
	v_mfma_f32_16x16x32_bf16 v[32:35], v[206:209], v[190:193], v[32:35]
	s_mov_b32 m0, s15
	v_lshl_add_u64 v[216:217], s[10:11], 0, v[162:163]
	s_barrier
; #define PG8_STAGE(bufoff, gbase, voff) do { _Pragma("unroll") for (int _i = 0; _i < 2; ++_i) \
;     __builtin_amdgcn_global_load_lds((const unsigned*)((const char*)(gbase) + (voff)[_i]), (LAS unsigned*)(lds + (bufoff) + ldsw + _i * 8192), 16, 0, 0); } while (0)
; #define PG8_LDA(dst, b, h) do { _Pragma("unroll") for (int m = 0; m < 4; ++m) _Pragma("unroll") for (int k = 0; k < 2; ++k) dst[m][k] = *(const LAS bf16x8*)(lds + PG8_SA(b, h) + aoff + m * 2048 + k * 1024); } while (0)
; #define PG8_LDB(dst, b, h) do { _Pragma("unroll") for (int n = 0; n < 2; ++n) _Pragma("unroll") for (int k = 0; k < 2; ++k) dst[n][k] = *(const LAS bf16x8*)(lds + PG8_SB(b, h) + boff + n * 2048 + k * 1024); } while (0)
; #define PG8_MMA(ai, bj, At, Bt) do { __builtin_amdgcn_s_setprio(1); _Pragma("unroll") for (int m = 0; m < 4; ++m) _Pragma("unroll") for (int n = 0; n < 2; ++n) _Pragma("unroll") for (int k = 0; k < 2; ++k) \
;     acc[ai][bj][m][n] = __builtin_amdgcn_mfma_f32_16x16x32_bf16(Bt[n][k], At[m][k], acc[ai][bj][m][n], 0, 0, 0); __builtin_amdgcn_s_setprio(0); } while (0)
; #define PG8_WAIT_V(n) asm volatile("s_waitcnt vmcnt(" #n ")" ::: "memory")
; #define PG8_WAIT_L(n) asm volatile("s_waitcnt lgkmcnt(" #n ")" ::: "memory")
; #define PG8_BAR __builtin_amdgcn_s_barrier()
; #define PG8_SCHED __builtin_amdgcn_sched_barrier(0)
; template <class Epi>
; __device__ __forceinline__ void gemm_phase(LAS unsigned char* lds, const Gemm g, const StaticOrder& S, const Epi& E) {
;     ...
;       PG8_LDA(At, 0, 1); PG8_STAGE(PG8_SA(0, 0), a2, voffA);
;       PG8_BAR; PG8_WAIT_L(0); PG8_MMA(1, 0, At, B0); PG8_BAR; PG8_SCHED;
;       PG8_STAGE(PG8_SB(0, 1), b2 + hstep, voffB);
;       PG8_WAIT_V(6); PG8_BAR; PG8_MMA(1, 1, At, B1); PG8_BAR;
;       PG8_LDB(B0, 1, 0); PG8_SCHED; PG8_LDA(At, 1, 0); PG8_STAGE(PG8_SA(0, 1), a2 + hstep, voffA);
;       PG8_WAIT_L(8); PG8_BAR; PG8_WAIT_L(0); PG8_MMA(0, 0, At, B0); PG8_BAR; PG8_SCHED;
;       PG8_LDB(B1, 1, 1); PG8_STAGE(PG8_SB(1, 0), b3, voffB);
;       PG8_BAR; PG8_WAIT_L(0); PG8_MMA(0, 1, At, B1); PG8_BAR;
;       PG8_LDA(At, 1, 1); PG8_STAGE(PG8_SA(1, 0), a3, voffA);
	ds_read_b128 v[146:149], v189 offset:16384
	ds_read_b128 v[150:153], v189 offset:17408
	ds_read_b128 v[154:157], v189 offset:18432
	ds_read_b128 v[158:161], v189 offset:19456
	ds_read_b128 v[174:177], v189 offset:20480
	ds_read_b128 v[178:181], v189 offset:21504
	ds_read_b128 v[182:185], v189 offset:22528
	ds_read_b128 v[190:193], v189 offset:23552
	global_load_lds_dwordx4 v[216:217], off
	v_lshl_add_u64 v[232:233], s[10:11], 0, v[166:167]
	s_mov_b32 m0, s84
	s_nop 0
	global_load_lds_dwordx4 v[232:233], off
	s_barrier
	s_waitcnt lgkmcnt(0)
	s_waitcnt lgkmcnt(0)
	v_mfma_f32_16x16x32_bf16 v[94:97], v[130:133], v[146:149], v[94:97]
	v_mfma_f32_16x16x32_bf16 v[90:93], v[138:141], v[146:149], v[90:93]
	v_mfma_f32_16x16x32_bf16 v[86:89], v[130:133], v[154:157], v[86:89]
	v_mfma_f32_16x16x32_bf16 v[82:85], v[138:141], v[154:157], v[82:85]
	v_mfma_f32_16x16x32_bf16 v[76:79], v[130:133], v[174:177], v[76:79]
	v_mfma_f32_16x16x32_bf16 v[72:75], v[138:141], v[174:177], v[72:75]
	v_mfma_f32_16x16x32_bf16 v[68:71], v[130:133], v[182:185], v[68:71]
	v_mfma_f32_16x16x32_bf16 v[64:67], v[138:141], v[182:185], v[64:67]
	v_mfma_f32_16x16x32_bf16 v[94:97], v[134:137], v[150:153], v[94:97]
	v_mfma_f32_16x16x32_bf16 v[90:93], v[142:145], v[150:153], v[90:93]
	v_mfma_f32_16x16x32_bf16 v[86:89], v[134:137], v[158:161], v[86:89]
	v_mfma_f32_16x16x32_bf16 v[82:85], v[142:145], v[158:161], v[82:85]
	v_mfma_f32_16x16x32_bf16 v[76:79], v[134:137], v[178:181], v[76:79]
	v_mfma_f32_16x16x32_bf16 v[72:75], v[142:145], v[178:181], v[72:75]
	v_mfma_f32_16x16x32_bf16 v[68:71], v[134:137], v[190:193], v[68:71]
	v_mfma_f32_16x16x32_bf16 v[64:67], v[142:145], v[190:193], v[64:67]
	s_waitcnt vmcnt(10)
	s_barrier
	s_add_u32 s12, s12, s64
	s_addc_u32 s13, s13, 0
	s_add_i32 s77, s78, s14
	v_lshl_add_u64 v[236:237], s[12:13], 0, v[164:165]
	s_mov_b32 m0, s77
	v_lshl_add_u64 v[242:243], s[12:13], 0, v[168:169]
	global_load_lds_dwordx4 v[236:237], off
	s_add_i32 m0, s77, 0x2000
	s_nop 0
	global_load_lds_dwordx4 v[242:243], off
	v_add_u32_e32 v80, 0x18000, v187
	s_waitcnt vmcnt(6)
	s_barrier
	v_mfma_f32_16x16x32_bf16 v[28:31], v[194:197], v[146:149], v[28:31]
	v_mfma_f32_16x16x32_bf16 v[24:27], v[202:205], v[146:149], v[24:27]
	ds_read_b128 v[130:133], v80
	v_mfma_f32_16x16x32_bf16 v[20:23], v[194:197], v[154:157], v[20:23]
	v_mfma_f32_16x16x32_bf16 v[16:19], v[202:205], v[154:157], v[16:19]
	ds_read_b128 v[134:137], v80 offset:1024
	v_mfma_f32_16x16x32_bf16 v[12:15], v[194:197], v[174:177], v[12:15]
	v_mfma_f32_16x16x32_bf16 v[8:11], v[202:205], v[174:177], v[8:11]
	ds_read_b128 v[138:141], v80 offset:2048
	v_mfma_f32_16x16x32_bf16 v[4:7], v[194:197], v[182:185], v[4:7]
	v_mfma_f32_16x16x32_bf16 v[0:3], v[202:205], v[182:185], v[0:3]
	ds_read_b128 v[142:145], v80 offset:3072
	v_mfma_f32_16x16x32_bf16 v[28:31], v[198:201], v[150:153], v[28:31]
	v_mfma_f32_16x16x32_bf16 v[24:27], v[206:209], v[150:153], v[24:27]
	v_mfma_f32_16x16x32_bf16 v[20:23], v[198:201], v[158:161], v[20:23]
	v_mfma_f32_16x16x32_bf16 v[16:19], v[206:209], v[158:161], v[16:19]
	v_mfma_f32_16x16x32_bf16 v[12:15], v[198:201], v[178:181], v[12:15]
	v_mfma_f32_16x16x32_bf16 v[8:11], v[206:209], v[178:181], v[8:11]
	v_mfma_f32_16x16x32_bf16 v[4:7], v[198:201], v[190:193], v[4:7]
	v_mfma_f32_16x16x32_bf16 v[0:3], v[206:209], v[190:193], v[0:3]
	s_add_i32 s12, 0, 0x18000
	s_barrier
	s_add_u32 s10, s10, s64
	s_addc_u32 s11, s11, 0
	s_mov_b32 m0, s99
	v_lshl_add_u64 v[194:195], s[10:11], 0, v[162:163]
	ds_read_b128 v[146:149], v189 offset:32768
	ds_read_b128 v[150:153], v189 offset:33792
	ds_read_b128 v[154:157], v189 offset:34816
	ds_read_b128 v[158:161], v189 offset:35840
	ds_read_b128 v[174:177], v189 offset:36864
	ds_read_b128 v[178:181], v189 offset:37888
	ds_read_b128 v[182:185], v189 offset:38912
	ds_read_b128 v[190:193], v189 offset:39936
	global_load_lds_dwordx4 v[194:195], off
	v_lshl_add_u64 v[194:195], s[10:11], 0, v[166:167]
	s_mov_b32 m0, s33
	s_nop 0
	global_load_lds_dwordx4 v[194:195], off
	s_waitcnt lgkmcnt(8)
	s_barrier
	s_waitcnt lgkmcnt(0)
	s_waitcnt lgkmcnt(0)
	v_mfma_f32_16x16x32_bf16 v[126:129], v[130:133], v[146:149], v[126:129]
	v_mfma_f32_16x16x32_bf16 v[122:125], v[138:141], v[146:149], v[122:125]
	v_mfma_f32_16x16x32_bf16 v[118:121], v[130:133], v[154:157], v[118:121]
	v_mfma_f32_16x16x32_bf16 v[114:117], v[138:141], v[154:157], v[114:117]
	v_mfma_f32_16x16x32_bf16 v[110:113], v[130:133], v[174:177], v[110:113]
	v_mfma_f32_16x16x32_bf16 v[106:109], v[138:141], v[174:177], v[106:109]
	v_mfma_f32_16x16x32_bf16 v[102:105], v[130:133], v[182:185], v[102:105]
	v_mfma_f32_16x16x32_bf16 v[98:101], v[138:141], v[182:185], v[98:101]
	v_mfma_f32_16x16x32_bf16 v[126:129], v[134:137], v[150:153], v[126:129]
	v_mfma_f32_16x16x32_bf16 v[122:125], v[142:145], v[150:153], v[122:125]
	v_mfma_f32_16x16x32_bf16 v[118:121], v[134:137], v[158:161], v[118:121]
	v_mfma_f32_16x16x32_bf16 v[114:117], v[142:145], v[158:161], v[114:117]
	v_mfma_f32_16x16x32_bf16 v[110:113], v[134:137], v[178:181], v[110:113]
	v_mfma_f32_16x16x32_bf16 v[106:109], v[142:145], v[178:181], v[106:109]
	v_mfma_f32_16x16x32_bf16 v[102:105], v[134:137], v[190:193], v[102:105]
	v_mfma_f32_16x16x32_bf16 v[98:101], v[142:145], v[190:193], v[98:101]
	s_barrier
	s_add_i32 s10, 0, 0x1c000
	s_add_i32 s11, s12, s14
	v_add_u32_e32 v80, s10, v187
	v_lshl_add_u64 v[210:211], v[210:211], 0, s[90:91]
	s_mov_b32 m0, s11
	ds_read_b128 v[194:197], v80
	ds_read_b128 v[198:201], v80 offset:1024
	ds_read_b128 v[202:205], v80 offset:2048
	ds_read_b128 v[206:209], v80 offset:3072
	global_load_lds_dwordx4 v[210:211], off
	v_lshl_add_u64 v[210:211], v[212:213], 0, s[90:91]
	s_add_i32 m0, s11, 0x2000
	s_nop 0
	global_load_lds_dwordx4 v[210:211], off
	s_barrier
; #define PG8_STAGE(bufoff, gbase, voff) do { _Pragma("unroll") for (int _i = 0; _i < 2; ++_i) \
;     __builtin_amdgcn_global_load_lds((const unsigned*)((const char*)(gbase) + (voff)[_i]), (LAS unsigned*)(lds + (bufoff) + ldsw + _i * 8192), 16, 0, 0); } while (0)
; #define PG8_LDA(dst, b, h) do { _Pragma("unroll") for (int m = 0; m < 4; ++m) _Pragma("unroll") for (int k = 0; k < 2; ++k) dst[m][k] = *(const LAS bf16x8*)(lds + PG8_SA(b, h) + aoff + m * 2048 + k * 1024); } while (0)
; #define PG8_MMA(ai, bj, At, Bt) do { __builtin_amdgcn_s_setprio(1); _Pragma("unroll") for (int m = 0; m < 4; ++m) _Pragma("unroll") for (int n = 0; n < 2; ++n) _Pragma("unroll") for (int k = 0; k < 2; ++k) \
;     acc[ai][bj][m][n] = __builtin_amdgcn_mfma_f32_16x16x32_bf16(Bt[n][k], At[m][k], acc[ai][bj][m][n], 0, 0, 0); __builtin_amdgcn_s_setprio(0); } while (0)
; #define PG8_WAIT_V(n) asm volatile("s_waitcnt vmcnt(" #n ")" ::: "memory")
; #define PG8_WAIT_L(n) asm volatile("s_waitcnt lgkmcnt(" #n ")" ::: "memory")
; #define PG8_BAR __builtin_amdgcn_s_barrier()
; #define PG8_SCHED __builtin_amdgcn_sched_barrier(0)
; template <class Epi>
; __device__ __forceinline__ void gemm_phase(LAS unsigned char* lds, const Gemm g, const StaticOrder& S, const Epi& E) {
;     ...
;       PG8_BAR; PG8_WAIT_L(0); PG8_MMA(0, 1, At, B1); PG8_BAR;
;       PG8_LDA(At, 1, 1); PG8_STAGE(PG8_SA(1, 0), a3, voffA);
;       PG8_BAR; PG8_WAIT_L(0); PG8_MMA(1, 0, At, B0); PG8_BAR; PG8_SCHED;
;       PG8_STAGE(PG8_SB(1, 1), b3 + hstep, voffB);
;       PG8_WAIT_V(6); PG8_BAR; PG8_MMA(1, 1, At, B1); PG8_BAR;
;     }
;     E(acc, cur, wr, wc, fr, fq);
;     if (!has_next) break;
	s_waitcnt lgkmcnt(0)
	s_waitcnt lgkmcnt(0)
	v_mfma_f32_16x16x32_bf16 v[60:63], v[194:197], v[146:149], v[60:63]
	v_mfma_f32_16x16x32_bf16 v[56:59], v[202:205], v[146:149], v[56:59]
	v_mfma_f32_16x16x32_bf16 v[52:55], v[194:197], v[154:157], v[52:55]
	v_mfma_f32_16x16x32_bf16 v[48:51], v[202:205], v[154:157], v[48:51]
	v_mfma_f32_16x16x32_bf16 v[44:47], v[194:197], v[174:177], v[44:47]
	v_mfma_f32_16x16x32_bf16 v[40:43], v[202:205], v[174:177], v[40:43]
	v_mfma_f32_16x16x32_bf16 v[36:39], v[194:197], v[182:185], v[36:39]
	v_mfma_f32_16x16x32_bf16 v[32:35], v[202:205], v[182:185], v[32:35]
	v_mfma_f32_16x16x32_bf16 v[60:63], v[198:201], v[150:153], v[60:63]
	v_mfma_f32_16x16x32_bf16 v[56:59], v[206:209], v[150:153], v[56:59]
	v_mfma_f32_16x16x32_bf16 v[52:55], v[198:201], v[158:161], v[52:55]
	v_mfma_f32_16x16x32_bf16 v[48:51], v[206:209], v[158:161], v[48:51]
	v_mfma_f32_16x16x32_bf16 v[44:47], v[198:201], v[178:181], v[44:47]
	v_mfma_f32_16x16x32_bf16 v[40:43], v[206:209], v[178:181], v[40:43]
	v_mfma_f32_16x16x32_bf16 v[36:39], v[198:201], v[190:193], v[36:39]
	v_mfma_f32_16x16x32_bf16 v[32:35], v[206:209], v[190:193], v[32:35]
	s_mov_b32 m0, s29
	v_lshl_add_u64 v[210:211], v[216:217], 0, s[90:91]
	s_barrier
	ds_read_b128 v[146:149], v189 offset:49152
	ds_read_b128 v[150:153], v189 offset:50176
	ds_read_b128 v[154:157], v189 offset:51200
	ds_read_b128 v[158:161], v189 offset:52224
	ds_read_b128 v[174:177], v189 offset:53248
	ds_read_b128 v[178:181], v189 offset:54272
	ds_read_b128 v[182:185], v189 offset:55296
	ds_read_b128 v[190:193], v189 offset:56320
	global_load_lds_dwordx4 v[210:211], off
	v_lshl_add_u64 v[210:211], v[232:233], 0, s[90:91]
	s_mov_b32 m0, s20
	s_nop 0
	global_load_lds_dwordx4 v[210:211], off
	s_barrier
	s_waitcnt lgkmcnt(0)
	s_waitcnt lgkmcnt(0)
	v_mfma_f32_16x16x32_bf16 v[94:97], v[130:133], v[146:149], v[94:97]
	v_mfma_f32_16x16x32_bf16 v[90:93], v[138:141], v[146:149], v[90:93]
	v_mfma_f32_16x16x32_bf16 v[86:89], v[130:133], v[154:157], v[86:89]
	v_mfma_f32_16x16x32_bf16 v[82:85], v[138:141], v[154:157], v[82:85]
	v_mfma_f32_16x16x32_bf16 v[76:79], v[130:133], v[174:177], v[76:79]
	v_mfma_f32_16x16x32_bf16 v[72:75], v[138:141], v[174:177], v[72:75]
	v_mfma_f32_16x16x32_bf16 v[68:71], v[130:133], v[182:185], v[68:71]
	v_mfma_f32_16x16x32_bf16 v[64:67], v[138:141], v[182:185], v[64:67]
	v_mfma_f32_16x16x32_bf16 v[94:97], v[134:137], v[150:153], v[94:97]
	v_mfma_f32_16x16x32_bf16 v[90:93], v[142:145], v[150:153], v[90:93]
	v_mfma_f32_16x16x32_bf16 v[86:89], v[134:137], v[158:161], v[86:89]
	v_mfma_f32_16x16x32_bf16 v[82:85], v[142:145], v[158:161], v[82:85]
	v_mfma_f32_16x16x32_bf16 v[76:79], v[134:137], v[178:181], v[76:79]
	v_mfma_f32_16x16x32_bf16 v[72:75], v[142:145], v[178:181], v[72:75]
	v_mfma_f32_16x16x32_bf16 v[68:71], v[134:137], v[190:193], v[68:71]
	v_mfma_f32_16x16x32_bf16 v[64:67], v[142:145], v[190:193], v[64:67]
	s_waitcnt vmcnt(10)
	s_barrier
	s_add_i32 s10, s10, s14
	v_lshl_add_u64 v[130:131], v[236:237], 0, s[90:91]
	s_mov_b32 m0, s10
	s_nop 0
	global_load_lds_dwordx4 v[130:131], off
	v_lshl_add_u64 v[130:131], v[242:243], 0, s[90:91]
	s_add_i32 m0, s10, 0x2000
	s_nop 0
	global_load_lds_dwordx4 v[130:131], off
	v_add_u32_e32 v80, 0x10000, v187
	s_waitcnt vmcnt(6)
	s_barrier
	v_mfma_f32_16x16x32_bf16 v[28:31], v[194:197], v[146:149], v[28:31]
	v_mfma_f32_16x16x32_bf16 v[24:27], v[202:205], v[146:149], v[24:27]
	ds_read_b128 v[130:133], v80
	v_mfma_f32_16x16x32_bf16 v[20:23], v[194:197], v[154:157], v[20:23]
	v_mfma_f32_16x16x32_bf16 v[16:19], v[202:205], v[154:157], v[16:19]
	ds_read_b128 v[134:137], v80 offset:1024
	v_mfma_f32_16x16x32_bf16 v[12:15], v[194:197], v[174:177], v[12:15]
	v_mfma_f32_16x16x32_bf16 v[8:11], v[202:205], v[174:177], v[8:11]
	ds_read_b128 v[138:141], v80 offset:2048
	v_mfma_f32_16x16x32_bf16 v[4:7], v[194:197], v[182:185], v[4:7]
	v_mfma_f32_16x16x32_bf16 v[0:3], v[202:205], v[182:185], v[0:3]
	ds_read_b128 v[142:145], v80 offset:3072
	v_mfma_f32_16x16x32_bf16 v[28:31], v[198:201], v[150:153], v[28:31]
	v_mfma_f32_16x16x32_bf16 v[24:27], v[206:209], v[150:153], v[24:27]
	v_mfma_f32_16x16x32_bf16 v[20:23], v[198:201], v[158:161], v[20:23]
	v_mfma_f32_16x16x32_bf16 v[16:19], v[206:209], v[158:161], v[16:19]
	v_mfma_f32_16x16x32_bf16 v[12:15], v[198:201], v[178:181], v[12:15]
	v_mfma_f32_16x16x32_bf16 v[8:11], v[206:209], v[178:181], v[8:11]
	v_mfma_f32_16x16x32_bf16 v[4:7], v[198:201], v[190:193], v[4:7]
	v_mfma_f32_16x16x32_bf16 v[0:3], v[206:209], v[190:193], v[0:3]
	s_add_u32 s74, s74, 0x100
	s_addc_u32 s75, s75, 0
	s_add_u32 s0, s0, 0x100
	s_addc_u32 s1, s1, 0
	s_cmp_ge_u32 s76, s2
	s_mov_b32 s10, s76
	s_barrier
	s_cbranch_scc0 .LBB0_56
	s_waitcnt lgkmcnt(0)
	s_cmp_lg_u32 s71, 0
	s_cselect_b64 s[0:1], -1, 0
	s_cmp_eq_u32 s71, 0
	s_cselect_b32 s10, s73, s72
	s_cselect_b32 s11, s72, s73
	s_lshl_b32 s71, s10, 8
	s_add_i32 s71, s71, s28
	v_or_b32_e32 v176, s71, v186
	v_lshl_or_b32 v174, s11, 8, v188
	s_cmp_lt_i32 s98, 2
	s_mov_b64 s[10:11], -1
	s_cbranch_scc1 .LBB0_151
	s_cmp_lt_i32 s98, 4
	s_cbranch_scc1 .LBB0_84
	s_cmp_lt_i32 s98, 5
	s_cbranch_scc1 .LBB0_65
	s_cmp_lg_u32 s98, 5
	s_cbranch_scc0 .LBB0_62
; __device__ __forceinline__ float lo16(unsigned v) { return __uint_as_float(v << 16); }
; __device__ __forceinline__ float hi16(unsigned v) { return __uint_as_float(v & 0xffff0000u); }
;   __device__ __forceinline__ void operator()(const f32x4 (&acc)[2][2][4][2], const pg8::Unit& u, int wr, int wc, int fr, int fq) const {
;     ...
;       float* xo = P->out + (size_t)slice * TS * DM; const u16* x2b = (const u16*)(ws + O_X2B) + (size_t)slice * TS * DM;
; #pragma unroll
;       for (int ai = 0; ai < 2; ++ai) {
;         u32x4 xv[4][2];
; #pragma unroll
;         for (int m = 0; m < 4; ++m)
; #pragma unroll
;           for (int bj = 0; bj < 2; ++bj) xv[m][bj] = *(const u32x4*)(x2b + (size_t)(row0 + ai * 128 + m * 16) * DM + col0 + bj * 128);
;         __builtin_amdgcn_sched_barrier(0);
; #pragma unroll
;         for (int m = 0; m < 4; ++m) {
;           const int row = row0 + ai * 128 + m * 16;
; #pragma unroll
;           for (int bj = 0; bj < 2; ++bj) {
;             float* d = xo + (size_t)row * DM + col0 + bj * 128;
;             const u32x4 x4 = xv[m][bj];
;             f32x4 o0 = acc[ai][bj][m][0], o1 = acc[ai][bj][m][1];
;             o0[0] += lo16(x4.x); o0[1] += hi16(x4.x); o0[2] += lo16(x4.y); o0[3] += hi16(x4.y); o1[0] += lo16(x4.z); o1[1] += hi16(x4.z); o1[2] += lo16(x4.w); o1[3] += hi16(x4.w);
;             *(f32x4*)d = o0; *(f32x4*)(d + 4) = o1;
;           }
;         }
	v_readlane_b32 s10, v254, 18
	v_ashrrev_i32_e32 v175, 31, v174
	v_readlane_b32 s11, v254, 19
	v_ashrrev_i32_e32 v177, 31, v176
	v_lshlrev_b64 v[130:131], 11, v[176:177]
	v_lshl_add_u64 v[136:137], v[174:175], 1, s[10:11]
	v_or_b32_e32 v190, 16, v176
	v_lshl_add_u64 v[130:131], v[136:137], 0, v[130:131]
	v_ashrrev_i32_e32 v191, 31, v190
	flat_load_dwordx4 v[138:141], v[130:131]
	flat_load_dwordx4 v[142:145], v[130:131] offset:256
	v_lshlrev_b64 v[130:131], 11, v[190:191]
	v_or_b32_e32 v192, 32, v176
	v_lshl_add_u64 v[130:131], v[136:137], 0, v[130:131]
	v_ashrrev_i32_e32 v193, 31, v192
	flat_load_dwordx4 v[146:149], v[130:131]
	flat_load_dwordx4 v[150:153], v[130:131] offset:256
	v_lshlrev_b64 v[130:131], 11, v[192:193]
	v_or_b32_e32 v194, 48, v176
	v_lshl_add_u64 v[130:131], v[136:137], 0, v[130:131]
	v_ashrrev_i32_e32 v195, 31, v194
	flat_load_dwordx4 v[154:157], v[130:131]
	flat_load_dwordx4 v[158:161], v[130:131] offset:256
	v_lshlrev_b64 v[130:131], 11, v[194:195]
	v_lshl_add_u64 v[130:131], v[136:137], 0, v[130:131]
	flat_load_dwordx4 v[178:181], v[130:131]
	s_nop 0
	flat_load_dwordx4 v[130:133], v[130:131] offset:256
	v_readlane_b32 s10, v254, 20
	v_readlane_b32 s11, v254, 21
	s_nop 1
	v_lshl_add_u64 v[134:135], v[174:175], 2, s[10:11]
	v_lshlrev_b64 v[182:183], 12, v[176:177]
	v_lshl_add_u64 v[196:197], v[134:135], 0, v[182:183]
	s_waitcnt vmcnt(0) lgkmcnt(0)
	v_lshlrev_b32_e32 v182, 16, v138
	v_and_b32_e32 v183, 0xffff0000, v138
	v_lshlrev_b32_e32 v138, 16, v139
	v_and_b32_e32 v139, 0xffff0000, v139
	v_pk_add_f32 v[184:185], v[128:129], v[138:139]
	v_lshlrev_b32_e32 v138, 16, v140
	v_and_b32_e32 v139, 0xffff0000, v140
	v_lshlrev_b32_e32 v140, 16, v141
	v_and_b32_e32 v141, 0xffff0000, v141
	v_pk_add_f32 v[182:183], v[126:127], v[182:183]
	v_pk_add_f32 v[138:139], v[122:123], v[138:139]
	v_pk_add_f32 v[140:141], v[124:125], v[140:141]
	global_store_dwordx4 v[196:197], v[182:185], off
	global_store_dwordx4 v[196:197], v[138:141], off offset:16
	s_nop 1
	v_lshlrev_b32_e32 v138, 16, v142
	v_and_b32_e32 v139, 0xffff0000, v142
	v_lshlrev_b32_e32 v140, 16, v143
	v_and_b32_e32 v141, 0xffff0000, v143
	v_pk_add_f32 v[138:139], v[60:61], v[138:139]
	v_pk_add_f32 v[140:141], v[62:63], v[140:141]
	v_lshlrev_b32_e32 v142, 16, v144
	v_and_b32_e32 v143, 0xffff0000, v144
	v_lshlrev_b32_e32 v144, 16, v145
	v_and_b32_e32 v145, 0xffff0000, v145
	v_pk_add_f32 v[142:143], v[56:57], v[142:143]
	v_pk_add_f32 v[144:145], v[58:59], v[144:145]
	global_store_dwordx4 v[196:197], v[138:141], off offset:512
	global_store_dwordx4 v[196:197], v[142:145], off offset:528
	s_nop 0
	v_lshlrev_b64 v[138:139], 12, v[190:191]
	v_lshl_add_u64 v[182:183], v[134:135], 0, v[138:139]
	v_lshlrev_b32_e32 v138, 16, v146
	v_and_b32_e32 v139, 0xffff0000, v146
	v_lshlrev_b32_e32 v140, 16, v147
	v_and_b32_e32 v141, 0xffff0000, v147
	v_pk_add_f32 v[138:139], v[118:119], v[138:139]
	v_pk_add_f32 v[140:141], v[120:121], v[140:141]
	v_lshlrev_b32_e32 v142, 16, v148
	v_and_b32_e32 v143, 0xffff0000, v148
	v_lshlrev_b32_e32 v144, 16, v149
	v_and_b32_e32 v145, 0xffff0000, v149
	v_pk_add_f32 v[142:143], v[114:115], v[142:143]
	v_pk_add_f32 v[144:145], v[116:117], v[144:145]
	global_store_dwordx4 v[182:183], v[138:141], off
	global_store_dwordx4 v[182:183], v[142:145], off offset:16
	s_nop 0
	v_lshlrev_b32_e32 v138, 16, v150
	v_and_b32_e32 v139, 0xffff0000, v150
	v_lshlrev_b32_e32 v140, 16, v151
	v_and_b32_e32 v141, 0xffff0000, v151
	v_pk_add_f32 v[138:139], v[52:53], v[138:139]
	v_pk_add_f32 v[140:141], v[54:55], v[140:141]
	v_lshlrev_b32_e32 v142, 16, v152
	v_and_b32_e32 v143, 0xffff0000, v152
	v_lshlrev_b32_e32 v144, 16, v153
	v_and_b32_e32 v145, 0xffff0000, v153
	v_pk_add_f32 v[142:143], v[48:49], v[142:143]
	v_pk_add_f32 v[144:145], v[50:51], v[144:145]
	global_store_dwordx4 v[182:183], v[138:141], off offset:512
	global_store_dwordx4 v[182:183], v[142:145], off offset:528
	s_nop 0
	v_lshlrev_b64 v[138:139], 12, v[192:193]
	v_lshl_add_u64 v[146:147], v[134:135], 0, v[138:139]
	v_lshlrev_b32_e32 v138, 16, v154
	v_and_b32_e32 v139, 0xffff0000, v154
	v_lshlrev_b32_e32 v140, 16, v155
	v_and_b32_e32 v141, 0xffff0000, v155
	v_pk_add_f32 v[138:139], v[110:111], v[138:139]
	v_pk_add_f32 v[140:141], v[112:113], v[140:141]
	v_lshlrev_b32_e32 v142, 16, v156
	v_and_b32_e32 v143, 0xffff0000, v156
	v_lshlrev_b32_e32 v144, 16, v157
	v_and_b32_e32 v145, 0xffff0000, v157
	v_pk_add_f32 v[142:143], v[106:107], v[142:143]
	v_pk_add_f32 v[144:145], v[108:109], v[144:145]
	global_store_dwordx4 v[146:147], v[138:141], off
	global_store_dwordx4 v[146:147], v[142:145], off offset:16
	s_nop 0
	v_lshlrev_b32_e32 v138, 16, v158
	v_and_b32_e32 v139, 0xffff0000, v158
	v_lshlrev_b32_e32 v140, 16, v159
	v_and_b32_e32 v141, 0xffff0000, v159
	v_pk_add_f32 v[138:139], v[44:45], v[138:139]
	v_pk_add_f32 v[140:141], v[46:47], v[140:141]
	v_lshlrev_b32_e32 v142, 16, v160
	v_and_b32_e32 v143, 0xffff0000, v160
	v_lshlrev_b32_e32 v144, 16, v161
	v_and_b32_e32 v145, 0xffff0000, v161
	v_pk_add_f32 v[142:143], v[40:41], v[142:143]
	v_pk_add_f32 v[144:145], v[42:43], v[144:145]
	global_store_dwordx4 v[146:147], v[138:141], off offset:512
	global_store_dwordx4 v[146:147], v[142:145], off offset:528
	s_nop 0
	v_lshlrev_b64 v[138:139], 12, v[194:195]
	v_lshl_add_u64 v[146:147], v[134:135], 0, v[138:139]
	v_lshlrev_b32_e32 v138, 16, v178
	v_and_b32_e32 v139, 0xffff0000, v178
	v_lshlrev_b32_e32 v140, 16, v179
	v_and_b32_e32 v141, 0xffff0000, v179
	v_pk_add_f32 v[138:139], v[102:103], v[138:139]
	v_pk_add_f32 v[140:141], v[104:105], v[140:141]
	v_lshlrev_b32_e32 v142, 16, v180
	v_and_b32_e32 v143, 0xffff0000, v180
	v_lshlrev_b32_e32 v144, 16, v181
; __device__ __forceinline__ float lo16(unsigned v) { return __uint_as_float(v << 16); }
; __device__ __forceinline__ float hi16(unsigned v) { return __uint_as_float(v & 0xffff0000u); }
;   __device__ __forceinline__ void operator()(const f32x4 (&acc)[2][2][4][2], const pg8::Unit& u, int wr, int wc, int fr, int fq) const {
;     ...
;       float* xo = P->out + (size_t)slice * TS * DM; const u16* x2b = (const u16*)(ws + O_X2B) + (size_t)slice * TS * DM;
; #pragma unroll
;       for (int ai = 0; ai < 2; ++ai) {
;         u32x4 xv[4][2];
; #pragma unroll
;         for (int m = 0; m < 4; ++m)
; #pragma unroll
;           for (int bj = 0; bj < 2; ++bj) xv[m][bj] = *(const u32x4*)(x2b + (size_t)(row0 + ai * 128 + m * 16) * DM + col0 + bj * 128);
;         __builtin_amdgcn_sched_barrier(0);
; #pragma unroll
;         for (int m = 0; m < 4; ++m) {
;           const int row = row0 + ai * 128 + m * 16;
; #pragma unroll
;           for (int bj = 0; bj < 2; ++bj) {
;             float* d = xo + (size_t)row * DM + col0 + bj * 128;
;             const u32x4 x4 = xv[m][bj];
;             f32x4 o0 = acc[ai][bj][m][0], o1 = acc[ai][bj][m][1];
;             o0[0] += lo16(x4.x); o0[1] += hi16(x4.x); o0[2] += lo16(x4.y); o0[3] += hi16(x4.y); o1[0] += lo16(x4.z); o1[1] += hi16(x4.z); o1[2] += lo16(x4.w); o1[3] += hi16(x4.w);
;             *(f32x4*)d = o0; *(f32x4*)(d + 4) = o1;
;           }
;         }
	v_and_b32_e32 v145, 0xffff0000, v181
	v_pk_add_f32 v[142:143], v[98:99], v[142:143]
	v_pk_add_f32 v[144:145], v[100:101], v[144:145]
	global_store_dwordx4 v[146:147], v[138:141], off
	global_store_dwordx4 v[146:147], v[142:145], off offset:16
	s_nop 0
	v_lshlrev_b32_e32 v138, 16, v130
	v_and_b32_e32 v139, 0xffff0000, v130
	v_lshlrev_b32_e32 v130, 16, v131
	v_and_b32_e32 v131, 0xffff0000, v131
	v_pk_add_f32 v[138:139], v[36:37], v[138:139]
	v_pk_add_f32 v[140:141], v[38:39], v[130:131]
	v_lshlrev_b32_e32 v130, 16, v132
	v_and_b32_e32 v131, 0xffff0000, v132
	v_lshlrev_b32_e32 v132, 16, v133
	v_and_b32_e32 v133, 0xffff0000, v133
	v_pk_add_f32 v[130:131], v[32:33], v[130:131]
	v_pk_add_f32 v[132:133], v[34:35], v[132:133]
	global_store_dwordx4 v[146:147], v[138:141], off offset:512
	global_store_dwordx4 v[146:147], v[130:133], off offset:528
	v_add_u32_e32 v182, 0x80, v176
	v_ashrrev_i32_e32 v183, 31, v182
	v_lshlrev_b64 v[130:131], 11, v[182:183]
	v_add_u32_e32 v190, 0x90, v176
	v_lshl_add_u64 v[130:131], v[136:137], 0, v[130:131]
	v_ashrrev_i32_e32 v191, 31, v190
	flat_load_dwordx4 v[138:141], v[130:131]
	flat_load_dwordx4 v[142:145], v[130:131] offset:256
	v_lshlrev_b64 v[130:131], 11, v[190:191]
	v_add_u32_e32 v192, 0xa0, v176
	v_lshl_add_u64 v[130:131], v[136:137], 0, v[130:131]
	v_ashrrev_i32_e32 v193, 31, v192
	flat_load_dwordx4 v[146:149], v[130:131]
	flat_load_dwordx4 v[150:153], v[130:131] offset:256
	v_lshlrev_b64 v[130:131], 11, v[192:193]
	v_add_u32_e32 v194, 0xb0, v176
	v_lshl_add_u64 v[130:131], v[136:137], 0, v[130:131]
	v_ashrrev_i32_e32 v195, 31, v194
	flat_load_dwordx4 v[154:157], v[130:131]
	flat_load_dwordx4 v[158:161], v[130:131] offset:256
	v_lshlrev_b64 v[130:131], 11, v[194:195]
	v_lshl_add_u64 v[130:131], v[136:137], 0, v[130:131]
	flat_load_dwordx4 v[178:181], v[130:131]
	s_nop 0
	flat_load_dwordx4 v[130:133], v[130:131] offset:256
	v_lshlrev_b64 v[136:137], 12, v[182:183]
	v_lshl_add_u64 v[196:197], v[134:135], 0, v[136:137]
	s_waitcnt vmcnt(0) lgkmcnt(0)
; __device__ __forceinline__ float lo16(unsigned v) { return __uint_as_float(v << 16); }
; __device__ __forceinline__ float hi16(unsigned v) { return __uint_as_float(v & 0xffff0000u); }
;   __device__ __forceinline__ void operator()(const f32x4 (&acc)[2][2][4][2], const pg8::Unit& u, int wr, int wc, int fr, int fq) const {
;     ...
; #pragma unroll
;         for (int m = 0; m < 4; ++m) {
;           const int row = row0 + ai * 128 + m * 16;
; #pragma unroll
;           for (int bj = 0; bj < 2; ++bj) {
;             float* d = xo + (size_t)row * DM + col0 + bj * 128;
;             const u32x4 x4 = xv[m][bj];
;             f32x4 o0 = acc[ai][bj][m][0], o1 = acc[ai][bj][m][1];
;             o0[0] += lo16(x4.x); o0[1] += hi16(x4.x); o0[2] += lo16(x4.y); o0[3] += hi16(x4.y); o1[0] += lo16(x4.z); o1[1] += hi16(x4.z); o1[2] += lo16(x4.w); o1[3] += hi16(x4.w);
;             *(f32x4*)d = o0; *(f32x4*)(d + 4) = o1;
;           }
;         }
	v_lshlrev_b32_e32 v136, 16, v138
	v_and_b32_e32 v137, 0xffff0000, v138
	v_lshlrev_b32_e32 v138, 16, v139
	v_and_b32_e32 v139, 0xffff0000, v139
	v_pk_add_f32 v[136:137], v[94:95], v[136:137]
	v_pk_add_f32 v[138:139], v[96:97], v[138:139]
	v_lshlrev_b32_e32 v182, 16, v140
	v_and_b32_e32 v183, 0xffff0000, v140
	v_lshlrev_b32_e32 v140, 16, v141
	v_and_b32_e32 v141, 0xffff0000, v141
	v_pk_add_f32 v[182:183], v[90:91], v[182:183]
	v_pk_add_f32 v[184:185], v[92:93], v[140:141]
	global_store_dwordx4 v[196:197], v[136:139], off
	global_store_dwordx4 v[196:197], v[182:185], off offset:16
	v_lshlrev_b32_e32 v140, 16, v144
	v_lshlrev_b32_e32 v136, 16, v142
	v_and_b32_e32 v137, 0xffff0000, v142
	v_lshlrev_b32_e32 v138, 16, v143
	v_and_b32_e32 v139, 0xffff0000, v143
	v_pk_add_f32 v[136:137], v[28:29], v[136:137]
	v_pk_add_f32 v[138:139], v[30:31], v[138:139]
	v_and_b32_e32 v141, 0xffff0000, v144
	v_lshlrev_b32_e32 v142, 16, v145
	v_and_b32_e32 v143, 0xffff0000, v145
	v_pk_add_f32 v[140:141], v[24:25], v[140:141]
	v_pk_add_f32 v[142:143], v[26:27], v[142:143]
	global_store_dwordx4 v[196:197], v[136:139], off offset:512
	global_store_dwordx4 v[196:197], v[140:143], off offset:528
	s_nop 0
	v_lshlrev_b64 v[136:137], 12, v[190:191]
	v_lshl_add_u64 v[144:145], v[134:135], 0, v[136:137]
	v_lshlrev_b32_e32 v136, 16, v146
	v_and_b32_e32 v137, 0xffff0000, v146
	v_lshlrev_b32_e32 v138, 16, v147
	v_and_b32_e32 v139, 0xffff0000, v147
	v_pk_add_f32 v[136:137], v[86:87], v[136:137]
	v_pk_add_f32 v[138:139], v[88:89], v[138:139]
	v_lshlrev_b32_e32 v140, 16, v148
	v_and_b32_e32 v141, 0xffff0000, v148
	v_lshlrev_b32_e32 v142, 16, v149
	v_and_b32_e32 v143, 0xffff0000, v149
	v_pk_add_f32 v[140:141], v[82:83], v[140:141]
	v_pk_add_f32 v[142:143], v[84:85], v[142:143]
	global_store_dwordx4 v[144:145], v[136:139], off
	global_store_dwordx4 v[144:145], v[140:143], off offset:16
	s_nop 0
	v_lshlrev_b32_e32 v136, 16, v150
	v_and_b32_e32 v137, 0xffff0000, v150
	v_lshlrev_b32_e32 v138, 16, v151
	v_and_b32_e32 v139, 0xffff0000, v151
	v_pk_add_f32 v[136:137], v[20:21], v[136:137]
	v_pk_add_f32 v[138:139], v[22:23], v[138:139]
	v_lshlrev_b32_e32 v140, 16, v152
	v_and_b32_e32 v141, 0xffff0000, v152
	v_lshlrev_b32_e32 v142, 16, v153
	v_and_b32_e32 v143, 0xffff0000, v153
	v_pk_add_f32 v[140:141], v[16:17], v[140:141]
	v_pk_add_f32 v[142:143], v[18:19], v[142:143]
	global_store_dwordx4 v[144:145], v[136:139], off offset:512
	global_store_dwordx4 v[144:145], v[140:143], off offset:528
	s_nop 0
	v_lshlrev_b64 v[136:137], 12, v[192:193]
	v_lshl_add_u64 v[144:145], v[134:135], 0, v[136:137]
	v_lshlrev_b32_e32 v136, 16, v154
	v_and_b32_e32 v137, 0xffff0000, v154
	v_lshlrev_b32_e32 v138, 16, v155
	v_and_b32_e32 v139, 0xffff0000, v155
	v_pk_add_f32 v[136:137], v[76:77], v[136:137]
	v_pk_add_f32 v[138:139], v[78:79], v[138:139]
	v_lshlrev_b32_e32 v140, 16, v156
	v_and_b32_e32 v141, 0xffff0000, v156
	v_lshlrev_b32_e32 v142, 16, v157
	v_and_b32_e32 v143, 0xffff0000, v157
	v_pk_add_f32 v[140:141], v[72:73], v[140:141]
	v_pk_add_f32 v[142:143], v[74:75], v[142:143]
	global_store_dwordx4 v[144:145], v[136:139], off
	global_store_dwordx4 v[144:145], v[140:143], off offset:16
	s_nop 0
	v_lshlrev_b32_e32 v136, 16, v158
	v_and_b32_e32 v137, 0xffff0000, v158
	v_lshlrev_b32_e32 v138, 16, v159
	v_and_b32_e32 v139, 0xffff0000, v159
	v_pk_add_f32 v[136:137], v[12:13], v[136:137]
	v_pk_add_f32 v[138:139], v[14:15], v[138:139]
	v_lshlrev_b32_e32 v140, 16, v160
	v_and_b32_e32 v141, 0xffff0000, v160
	v_lshlrev_b32_e32 v142, 16, v161
	v_and_b32_e32 v143, 0xffff0000, v161
	v_pk_add_f32 v[140:141], v[8:9], v[140:141]
	v_pk_add_f32 v[142:143], v[10:11], v[142:143]
	global_store_dwordx4 v[144:145], v[136:139], off offset:512
	global_store_dwordx4 v[144:145], v[140:143], off offset:528
	s_nop 0
	v_lshlrev_b64 v[136:137], 12, v[194:195]
	v_lshl_add_u64 v[142:143], v[134:135], 0, v[136:137]
	v_lshlrev_b32_e32 v134, 16, v178
	v_and_b32_e32 v135, 0xffff0000, v178
	v_lshlrev_b32_e32 v136, 16, v179
	v_and_b32_e32 v137, 0xffff0000, v179
	v_pk_add_f32 v[134:135], v[68:69], v[134:135]
	v_pk_add_f32 v[136:137], v[70:71], v[136:137]
	v_lshlrev_b32_e32 v138, 16, v180
	v_and_b32_e32 v139, 0xffff0000, v180
	v_lshlrev_b32_e32 v140, 16, v181
	v_and_b32_e32 v141, 0xffff0000, v181
	v_pk_add_f32 v[138:139], v[64:65], v[138:139]
	v_pk_add_f32 v[140:141], v[66:67], v[140:141]
	global_store_dwordx4 v[142:143], v[134:137], off
	global_store_dwordx4 v[142:143], v[138:141], off offset:16
	s_nop 0
	v_lshlrev_b32_e32 v134, 16, v130
	v_and_b32_e32 v135, 0xffff0000, v130
	v_lshlrev_b32_e32 v130, 16, v131
	v_and_b32_e32 v131, 0xffff0000, v131
	v_pk_add_f32 v[134:135], v[4:5], v[134:135]
	v_pk_add_f32 v[136:137], v[6:7], v[130:131]
	v_lshlrev_b32_e32 v130, 16, v132
	v_and_b32_e32 v131, 0xffff0000, v132
	v_lshlrev_b32_e32 v132, 16, v133
	v_and_b32_e32 v133, 0xffff0000, v133
	v_pk_add_f32 v[130:131], v[0:1], v[130:131]
	v_pk_add_f32 v[132:133], v[2:3], v[132:133]
	global_store_dwordx4 v[142:143], v[134:137], off offset:512
	global_store_dwordx4 v[142:143], v[130:133], off offset:528
	s_mov_b64 s[10:11], 0
